# chain gated-norm tail: 16 global_store_short per chunk become 8 global_store_dword (pack two column groups, swap halves with the neighbour lane via DPP + v_perm); loop-bottom wait vmcnt(8); on top of
# baseline (speedup 1.0000x reference)
.LBB0_1183:
	s_or_b64 exec, exec, s[0:1]
	v_mul_f32_e32 v120, 0x3fb8aa3b, v204
	v_exp_f32_e32 v204, v120
	s_waitcnt lgkmcnt(0)
	ds_read_b128 v[120:123], v188 offset:53248
	ds_read_b128 v[124:127], v188 offset:53312
	ds_read_b128 v[212:215], v191 offset:53248
	ds_read_b128 v[216:219], v191 offset:53312
	ds_read_b128 v[220:223], v189 offset:53248
	ds_read_b128 v[224:227], v189 offset:53312
	v_pk_mul_f32 v[54:55], v[54:55], v[204:205] op_sel_hi:[1,0]
	v_pk_mul_f32 v[52:53], v[52:53], v[204:205] op_sel_hi:[1,0]
	v_pk_mul_f32 v[58:59], v[58:59], v[204:205] op_sel_hi:[1,0]
	v_pk_mul_f32 v[56:57], v[56:57], v[204:205] op_sel_hi:[1,0]
	s_waitcnt lgkmcnt(0)
	v_mfma_f32_16x16x32_bf16 v[52:55], v[80:83], v[120:123], v[52:55]
	v_mul_f32_e64 v46, v46, v204
	v_mul_f32_e64 v47, v47, v204
	v_pk_mul_f32 v[44:45], v[44:45], v[204:205] op_sel_hi:[1,0]
	v_pk_mul_f32 v[38:39], v[38:39], v[204:205] op_sel_hi:[1,0]
	v_pk_mul_f32 v[36:37], v[36:37], v[204:205] op_sel_hi:[1,0]
	ds_read_b128 v[228:231], v187 offset:53248
	ds_read_b128 v[232:235], v187 offset:53312
	v_add_u32_e32 v255, v210, v199
	v_add3_u32 v255, v255, v200, v201
	ds_read_u16 v236, v255 offset:2048
	ds_read_u16 v237, v255 offset:2080
	ds_read_u16 v238, v255 offset:2112
	ds_read_u16 v239, v255 offset:2144
	ds_read_u16 v240, v255 offset:2176
	ds_read_u16 v241, v255 offset:2208
	ds_read_u16 v242, v255 offset:2240
	ds_read_u16 v243, v255 offset:2272
	ds_read_u16 v244, v255 offset:2304
	ds_read_u16 v245, v255 offset:2336
	ds_read_u16 v249, v255 offset:2368
	ds_read_u16 v250, v255 offset:2400
	ds_read_u16 v251, v255 offset:2432
	ds_read_u16 v252, v255 offset:2464
	ds_read_u16 v253, v255 offset:2496
	ds_read_u16 v254, v255 offset:2528
	v_mbcnt_lo_u32_b32 v255, -1, 0
	v_mbcnt_hi_u32_b32 v255, -1, v255
	v_and_b32_e32 v255, 1, v255
	s_mov_b32 s100, 0xfdfe0606
	v_mul_u32_u24_e32 v211, 30, v255
	v_mul_lo_u32 v255, v255, s100
	v_add_u32_e32 v255, 0x05040100, v255
	v_pk_mul_f32 v[62:63], v[62:63], v[204:205] op_sel_hi:[1,0]
	v_pk_mul_f32 v[60:61], v[60:61], v[204:205] op_sel_hi:[1,0]
	v_pk_mul_f32 v[66:67], v[66:67], v[204:205] op_sel_hi:[1,0]
	v_pk_mul_f32 v[64:65], v[64:65], v[204:205] op_sel_hi:[1,0]
	v_mfma_f32_16x16x32_bf16 v[56:59], v[72:75], v[120:123], v[56:59]
	v_mul_f32_e64 v34, v34, v204
	v_mul_f32_e64 v35, v35, v204
	v_pk_mul_f32 v[32:33], v[32:33], v[204:205] op_sel_hi:[1,0]
	v_pk_mul_f32 v[70:71], v[70:71], v[204:205] op_sel_hi:[1,0]
	v_mfma_f32_16x16x32_bf16 v[44:47], v[80:83], v[212:215], v[44:47]
	v_mul_f32_e64 v68, v68, v204
	v_mul_f32_e64 v69, v69, v204
	s_waitcnt lgkmcnt(0)
	s_barrier
	v_mfma_f32_16x16x32_bf16 v[36:39], v[80:83], v[220:223], v[36:39]
	v_lshlrev_b32_e32 v236, 16, v236
	v_lshlrev_b32_e32 v237, 16, v237
	v_lshlrev_b32_e32 v238, 16, v238
	v_lshlrev_b32_e32 v239, 16, v239
	v_lshlrev_b32_e32 v240, 16, v240
	v_lshlrev_b32_e32 v241, 16, v241
	v_lshlrev_b32_e32 v242, 16, v242
	v_lshlrev_b32_e32 v243, 16, v243
	s_add_i32 s23, s23, 64
	s_addk_i32 s25, 0x1000
	v_mfma_f32_16x16x32_bf16 v[60:63], v[72:75], v[212:215], v[60:63]
	v_lshlrev_b32_e32 v244, 16, v244
	v_lshlrev_b32_e32 v245, 16, v245
	v_lshlrev_b32_e32 v249, 16, v249
	v_lshlrev_b32_e32 v250, 16, v250
	v_lshlrev_b32_e32 v251, 16, v251
	v_lshlrev_b32_e32 v252, 16, v252
	v_lshlrev_b32_e32 v253, 16, v253
	v_lshlrev_b32_e32 v254, 16, v254
	s_add_i32 s30, s30, 32
	s_add_i32 s26, s26, 16
	s_add_i32 s28, s28, 32
	v_mfma_f32_16x16x32_bf16 v[64:67], v[72:75], v[220:223], v[64:67]
	s_add_u32 s34, s34, 0x2000
	s_addc_u32 s35, s35, 0
	s_cmpk_eq_i32 s23, 0x780
	v_mfma_f32_16x16x32_bf16 v[52:55], v[84:87], v[124:127], v[52:55]
	v_mul_f32_e32 v212, 0xbfb8aa3b, v236
	v_mul_f32_e32 v213, 0xbfb8aa3b, v237
	v_mul_f32_e32 v214, 0xbfb8aa3b, v238
	v_mul_f32_e32 v215, 0xbfb8aa3b, v239
	v_mul_f32_e32 v220, 0xbfb8aa3b, v240
	v_mul_f32_e32 v221, 0xbfb8aa3b, v241
	v_mul_f32_e32 v222, 0xbfb8aa3b, v242
	v_mul_f32_e32 v223, 0xbfb8aa3b, v243
	v_mfma_f32_16x16x32_bf16 v[56:59], v[76:79], v[124:127], v[56:59]
	v_exp_f32_e32 v212, v212
	v_exp_f32_e32 v213, v213
	v_exp_f32_e32 v214, v214
	v_exp_f32_e32 v215, v215
	v_exp_f32_e32 v220, v220
	v_exp_f32_e32 v221, v221
	v_exp_f32_e32 v222, v222
	v_exp_f32_e32 v223, v223
	v_mfma_f32_16x16x32_bf16 v[44:47], v[84:87], v[216:219], v[44:47]
	v_add_f32_e32 v212, 1.0, v212
	v_add_f32_e32 v213, 1.0, v213
	v_add_f32_e32 v214, 1.0, v214
	v_add_f32_e32 v215, 1.0, v215
	v_add_f32_e32 v220, 1.0, v220
	v_add_f32_e32 v221, 1.0, v221
	v_add_f32_e32 v222, 1.0, v222
	v_add_f32_e32 v223, 1.0, v223
	v_mfma_f32_16x16x32_bf16 v[36:39], v[84:87], v[224:227], v[36:39]
	v_rcp_f32_e32 v212, v212
	v_rcp_f32_e32 v213, v213
	v_rcp_f32_e32 v214, v214
	v_rcp_f32_e32 v215, v215
	v_rcp_f32_e32 v220, v220
	v_rcp_f32_e32 v221, v221
	v_rcp_f32_e32 v222, v222
	v_rcp_f32_e32 v223, v223
	s_nop 5
	v_cvt_pk_bf16_f32 v120, v56, v57
	v_cvt_pk_bf16_f32 v121, v58, v59
	s_waitcnt lgkmcnt(0)
	v_mfma_f32_16x16x32_bf16 v[32:35], v[80:83], v[228:231], v[32:35]
	v_mul_f32_e32 v236, v212, v236
	v_mul_f32_e32 v237, v213, v237
	v_mul_f32_e32 v238, v214, v238
	v_mul_f32_e32 v239, v215, v239
	v_mul_f32_e32 v240, v220, v240
	v_mul_f32_e32 v241, v221, v241
	v_mul_f32_e32 v242, v222, v242
	v_mul_f32_e32 v243, v223, v243
	v_cvt_pk_bf16_f32 v80, v52, v53
	v_cvt_pk_bf16_f32 v81, v54, v55
	v_cvt_pk_bf16_f32 v82, v44, v45
	v_mfma_f32_16x16x32_bf16 v[60:63], v[76:79], v[216:219], v[60:63]
	v_mul_f32_e32 v212, 0xbfb8aa3b, v244
	v_mul_f32_e32 v213, 0xbfb8aa3b, v245
	v_mul_f32_e32 v214, 0xbfb8aa3b, v249
	v_mul_f32_e32 v215, 0xbfb8aa3b, v250
	v_mul_f32_e32 v220, 0xbfb8aa3b, v251
	v_mul_f32_e32 v221, 0xbfb8aa3b, v252
	v_mul_f32_e32 v222, 0xbfb8aa3b, v253
	v_mul_f32_e32 v223, 0xbfb8aa3b, v254
	v_cvt_pk_bf16_f32 v83, v46, v47
	ds_write2_b64 v173, v[80:81], v[120:121] offset1:4
	v_mfma_f32_16x16x32_bf16 v[64:67], v[76:79], v[224:227], v[64:67]
	v_exp_f32_e32 v212, v212
	v_exp_f32_e32 v213, v213
	v_exp_f32_e32 v214, v214
	v_exp_f32_e32 v215, v215
	v_exp_f32_e32 v220, v220
	v_exp_f32_e32 v221, v221
	v_exp_f32_e32 v222, v222
	v_exp_f32_e32 v223, v223
	v_mfma_f32_16x16x32_bf16 v[68:71], v[72:75], v[228:231], v[68:71]
	v_add_f32_e32 v212, 1.0, v212
	v_add_f32_e32 v213, 1.0, v213
	v_add_f32_e32 v214, 1.0, v214
	v_add_f32_e32 v215, 1.0, v215
	v_add_f32_e32 v220, 1.0, v220
	v_add_f32_e32 v221, 1.0, v221
	v_add_f32_e32 v222, 1.0, v222
	v_add_f32_e32 v223, 1.0, v223
	s_nop 3
	v_cvt_pk_bf16_f32 v80, v60, v61
	v_cvt_pk_bf16_f32 v81, v62, v63
	s_nop 0
	v_cvt_pk_bf16_f32 v72, v64, v65
	v_mfma_f32_16x16x32_bf16 v[32:35], v[84:87], v[232:235], v[32:35]
	v_rcp_f32_e32 v212, v212
	v_rcp_f32_e32 v213, v213
	v_rcp_f32_e32 v214, v214
	v_rcp_f32_e32 v215, v215
	v_rcp_f32_e32 v220, v220
	v_rcp_f32_e32 v221, v221
	v_rcp_f32_e32 v222, v222
	v_rcp_f32_e32 v223, v223
	v_cvt_pk_bf16_f32 v84, v36, v37
	v_cvt_pk_bf16_f32 v85, v38, v39
	v_cvt_pk_bf16_f32 v73, v66, v67
	v_mfma_f32_16x16x32_bf16 v[68:71], v[76:79], v[232:235], v[68:71]
	v_mul_f32_e32 v244, v212, v244
	v_mul_f32_e32 v245, v213, v245
	v_mul_f32_e32 v249, v214, v249
	v_mul_f32_e32 v250, v215, v250
	v_mul_f32_e32 v251, v220, v251
	v_mul_f32_e32 v252, v221, v252
	v_mul_f32_e32 v253, v222, v253
	v_mul_f32_e32 v254, v223, v254
	ds_write2_b64 v184, v[82:83], v[80:81] offset0:32 offset1:36
	ds_write2_b64 v185, v[84:85], v[72:73] offset0:64 offset1:68
	v_cvt_pk_bf16_f32 v86, v32, v33
	v_cvt_pk_bf16_f32 v87, v34, v35
	v_cvt_pk_bf16_f32 v72, v68, v69
	v_cvt_pk_bf16_f32 v73, v70, v71
	ds_write2_b64 v186, v[86:87], v[72:73] offset0:96 offset1:100
	ds_read_b128 v[72:75], v179
	ds_read_b128 v[76:79], v179 offset:256
	v_add_u32_e32 v80, 64, v209
	v_ashrrev_i32_e32 v81, 31, v80
	v_lshlrev_b64 v[80:81], 13, v[80:81]
	v_or_b32_e32 v80, v80, v211
	v_lshl_add_u64 v[80:81], v[156:157], 0, v[80:81]
	v_add_u32_e32 v82, 0x41, v209
	v_ashrrev_i32_e32 v83, 31, v82
	v_lshlrev_b64 v[82:83], 13, v[82:83]
	v_or_b32_e32 v82, v82, v211
	v_lshl_add_u64 v[82:83], v[156:157], 0, v[82:83]
	v_add_u32_e32 v84, 0x42, v209
	v_ashrrev_i32_e32 v85, 31, v84
	v_lshlrev_b64 v[84:85], 13, v[84:85]
	v_or_b32_e32 v84, v84, v211
	v_lshl_add_u64 v[84:85], v[156:157], 0, v[84:85]
	v_add_u32_e32 v86, 0x43, v209
	v_ashrrev_i32_e32 v87, 31, v86
	v_lshlrev_b64 v[86:87], 13, v[86:87]
	v_or_b32_e32 v86, v86, v211
	v_lshl_add_u64 v[86:87], v[156:157], 0, v[86:87]
	s_waitcnt lgkmcnt(0)
	v_pk_add_f32 v[72:73], v[72:73], v[76:77]
	v_pk_add_f32 v[74:75], v[74:75], v[78:79]
	v_mov_b64_e32 v[76:77], s[20:21]
	v_pk_fma_f32 v[72:73], v[72:73], s[18:19], v[76:77] op_sel_hi:[1,0,0]
	v_pk_fma_f32 v[74:75], v[74:75], s[18:19], v[76:77] op_sel_hi:[1,0,0]
	v_cmp_gt_f32_e64 s[0:1], s45, v72
	v_cmp_gt_f32_e64 s[98:99], s45, v73
	v_cmp_gt_f32_e64 s[100:101], s45, v74
	v_mul_f32_e32 v120, 0x4b800000, v72
	v_mul_f32_e32 v121, 0x4b800000, v73
	v_mul_f32_e32 v122, 0x4b800000, v74
	v_mul_f32_e32 v123, 0x4b800000, v75
	v_cndmask_b32_e64 v72, v72, v120, s[0:1]
	v_cndmask_b32_e64 v73, v73, v121, s[98:99]
	v_cndmask_b32_e64 v74, v74, v122, s[100:101]
	v_rsq_f32_e32 v72, v72
	v_rsq_f32_e32 v73, v73
	v_rsq_f32_e32 v74, v74
	s_nop 0
	v_mul_f32_e32 v120, 0x45800000, v72
	v_mul_f32_e32 v121, 0x45800000, v73
	v_mul_f32_e32 v122, 0x45800000, v74
	v_cndmask_b32_e64 v72, v72, v120, s[0:1]
	v_cndmask_b32_e64 v73, v73, v121, s[98:99]
	v_cndmask_b32_e64 v74, v74, v122, s[100:101]
	v_cmp_gt_f32_e64 s[0:1], s45, v75
	s_nop 0
	v_cndmask_b32_e64 v75, v75, v123, s[0:1]
	v_rsq_f32_e32 v75, v75
	v_mul_f32_e32 v120, v108, v72
	v_mul_f32_e32 v121, v112, v72
	v_mul_f32_e32 v122, v116, v72
	v_mul_f32_e32 v123, v104, v72
	v_mul_f32_e32 v120, v172, v120
	v_mul_f32_e32 v121, v171, v121
	v_mul_f32_e32 v122, v170, v122
	v_mul_f32_e32 v123, v169, v123
	v_mul_f32_e32 v120, v236, v120
	v_mul_f32_e32 v121, v237, v121
	v_mul_f32_e32 v122, v238, v122
	v_mul_f32_e32 v123, v239, v123
	v_cvt_pk_bf16_f32 v120, v120, v121
	v_cvt_pk_bf16_f32 v122, v122, v123
	s_nop 0
	v_mov_b32_dpp v121, v120 quad_perm:[1,0,3,2] row_mask:0xf bank_mask:0xf
	v_mov_b32_dpp v123, v122 quad_perm:[1,0,3,2] row_mask:0xf bank_mask:0xf
	v_perm_b32 v120, v121, v120, v255
	v_perm_b32 v122, v123, v122, v255
	global_store_dword v[80:81], v120, off
	global_store_dword v[80:81], v122, off offset:64
	v_mul_f32_e32 v124, 0x45800000, v75
	v_cndmask_b32_e64 v75, v75, v124, s[0:1]
	v_mul_f32_e32 v120, v109, v73
	v_mul_f32_e32 v121, v113, v73
	v_mul_f32_e32 v122, v117, v73
	v_mul_f32_e32 v123, v105, v73
	v_mul_f32_e32 v120, v172, v120
	v_mul_f32_e32 v121, v171, v121
	v_mul_f32_e32 v122, v170, v122
	v_mul_f32_e32 v123, v169, v123
	v_mul_f32_e32 v120, v240, v120
	v_mul_f32_e32 v121, v241, v121
	v_mul_f32_e32 v122, v242, v122
	v_mul_f32_e32 v123, v243, v123
	v_cvt_pk_bf16_f32 v120, v120, v121
	v_cvt_pk_bf16_f32 v122, v122, v123
	s_nop 0
	v_mov_b32_dpp v121, v120 quad_perm:[1,0,3,2] row_mask:0xf bank_mask:0xf
	v_mov_b32_dpp v123, v122 quad_perm:[1,0,3,2] row_mask:0xf bank_mask:0xf
	v_perm_b32 v120, v121, v120, v255
	v_perm_b32 v122, v123, v122, v255
	global_store_dword v[82:83], v120, off
	global_store_dword v[82:83], v122, off offset:64
	v_mul_f32_e32 v120, v110, v74
	v_mul_f32_e32 v121, v114, v74
	v_mul_f32_e32 v122, v118, v74
	v_mul_f32_e32 v123, v106, v74
	v_mul_f32_e32 v120, v172, v120
	v_mul_f32_e32 v121, v171, v121
	v_mul_f32_e32 v122, v170, v122
	v_mul_f32_e32 v123, v169, v123
	v_mul_f32_e32 v120, v244, v120
	v_mul_f32_e32 v121, v245, v121
	v_mul_f32_e32 v122, v249, v122
	v_mul_f32_e32 v123, v250, v123
	v_cvt_pk_bf16_f32 v120, v120, v121
	v_cvt_pk_bf16_f32 v122, v122, v123
	s_nop 0
	v_mov_b32_dpp v121, v120 quad_perm:[1,0,3,2] row_mask:0xf bank_mask:0xf
	v_mov_b32_dpp v123, v122 quad_perm:[1,0,3,2] row_mask:0xf bank_mask:0xf
	v_perm_b32 v120, v121, v120, v255
	v_perm_b32 v122, v123, v122, v255
	global_store_dword v[84:85], v120, off
	global_store_dword v[84:85], v122, off offset:64
	v_mul_f32_e32 v120, v111, v75
	v_mul_f32_e32 v121, v115, v75
	v_mul_f32_e32 v122, v119, v75
	v_mul_f32_e32 v123, v107, v75
	v_mul_f32_e32 v120, v172, v120
	v_mul_f32_e32 v121, v171, v121
	v_mul_f32_e32 v122, v170, v122
	v_mul_f32_e32 v123, v169, v123
	v_mul_f32_e32 v120, v251, v120
	v_mul_f32_e32 v121, v252, v121
	v_mul_f32_e32 v122, v253, v122
	v_mul_f32_e32 v123, v254, v123
	v_cvt_pk_bf16_f32 v120, v120, v121
	v_cvt_pk_bf16_f32 v122, v122, v123
	s_nop 0
	v_mov_b32_dpp v121, v120 quad_perm:[1,0,3,2] row_mask:0xf bank_mask:0xf
	v_mov_b32_dpp v123, v122 quad_perm:[1,0,3,2] row_mask:0xf bank_mask:0xf
	v_perm_b32 v120, v121, v120, v255
	v_perm_b32 v122, v123, v122, v255
	global_store_dword v[86:87], v120, off
	global_store_dword v[86:87], v122, off offset:64
	s_waitcnt lgkmcnt(0)
	s_barrier
	s_cbranch_scc1 .LBB0_1185
	s_waitcnt vmcnt(8)
	v_mov_b64_e32 v[76:77], v[88:89]
	v_mov_b64_e32 v[72:73], v[92:93]
	v_mov_b64_e32 v[84:85], v[96:97]
	v_mov_b64_e32 v[80:81], v[100:101]
	v_mov_b64_e32 v[78:79], v[90:91]
	v_mov_b64_e32 v[74:75], v[94:95]
	v_mov_b64_e32 v[86:87], v[98:99]
	v_mov_b64_e32 v[82:83], v[102:103]
	v_mov_b32_e32 v204, v130
	s_branch .LBB0_1181
